# prompt GLA chains also through the LDS-staged hand-written sequential pass
# speedup vs baseline: 1.0208x; 1.0028x over previous
.LBB0_1409:
	s_and_b64 vcc, exec, s[0:1]
	s_cbranch_vccz .LBB0_1434
	s_add_i32 s13, s23, 0xfffffc00
	s_branch .Lgla_new
	s_add_i32 s8, s23, 0xfffffbe0
	v_mov_b32_e32 v12, v179
	s_mov_b64 s[0:1], 0
	s_lshr_b32 s19, s8, 3
	s_bfe_u32 s10, s23, 0x20001
	s_and_b32 s13, s23, 1
	s_add_u32 s20, s90, s0
	s_addc_u32 s21, s91, s1
	s_lshl_b32 s50, s19, 2
	s_mul_i32 s0, s13, 0x3000000
	s_add_u32 s38, s20, s0
	s_addc_u32 s41, s21, 0
	s_cmp_eq_u32 s13, 0
	s_cselect_b64 s[34:35], -1, 0
	s_add_u32 s8, s20, 0x2993d700
	s_addc_u32 s9, s21, 0
	s_add_u32 s0, s20, 0x2b13d700
	s_addc_u32 s1, s21, 0
	s_add_u32 s44, s20, 0x2c9fd700
	s_addc_u32 s45, s21, 0
	s_add_u32 s46, s20, 0x2c93d700
	s_addc_u32 s47, s21, 0
	s_lshl_b32 s40, s10, 9
	v_lshrrev_b32_e32 v0, 2, v12
	s_add_u32 s40, s38, s40
	v_and_b32_e32 v13, 63, v12
	v_ashrrev_i32_e32 v10, 6, v12
	s_waitcnt vmcnt(9)
	v_and_b32_e32 v44, 12, v0
	v_and_b32_e32 v0, 48, v12
	s_addc_u32 s41, s41, 0
	v_lshl_add_u64 v[46:47], s[46:47], 0, v[0:1]
	s_waitcnt vmcnt(1)
	v_lshl_add_u64 v[2:3], s[0:1], 0, v[0:1]
	v_lshl_add_u64 v[4:5], s[44:45], 0, v[0:1]
	s_waitcnt vmcnt(0)
	v_lshl_add_u64 v[6:7], s[40:41], 0, v[0:1]
	v_lshlrev_b32_e32 v0, 12, v10
	v_lshlrev_b32_e32 v11, 7, v13
	s_movk_i32 s2, 0xf000
	v_add3_u32 v8, v11, v0, s2
	v_ashrrev_i32_e32 v9, 31, v8
	v_lshlrev_b32_e32 v14, 11, v10
	v_lshl_add_u64 v[48:49], s[44:45], 0, v[8:9]
	v_add_u32_e32 v8, v14, v11
	v_lshlrev_b32_e32 v42, 5, v10
	v_add_u32_e32 v10, 0xfffff800, v8
	v_and_b32_e32 v45, 15, v12
	v_ashrrev_i32_e32 v11, 31, v10
	v_ashrrev_i32_e32 v9, 31, v8
	v_lshlrev_b32_e32 v0, 7, v12
	v_ashrrev_i32_e32 v43, 31, v42
	v_lshl_add_u64 v[50:51], s[0:1], 0, v[10:11]
	v_lshl_add_u64 v[52:53], s[8:9], 0, v[8:9]
	v_cmp_gt_u32_e32 vcc, 64, v12
	v_cmp_gt_u32_e64 s[0:1], 2, v13
	v_lshl_add_u64 v[54:55], s[46:47], 0, v[0:1]
	v_lshl_or_b32 v8, v45, 6, v14
	v_lshlrev_b32_e32 v0, 7, v45
	s_and_b64 s[44:45], vcc, s[0:1]
	v_ashrrev_i32_e32 v9, 31, v8
	v_lshl_add_u64 v[58:59], v[2:3], 0, v[0:1]
	v_lshl_add_u64 v[2:3], v[42:43], 2, v[6:7]
	s_mov_b64 s[0:1], 0x2e1fd700
	v_mov_b32_e32 v30, 0
	s_mov_b32 s28, 2
	v_lshl_or_b32 v64, s19, 8, v45
	v_cmp_lt_u32_e64 s[40:41], 15, v13
	v_cmp_lt_u32_e64 s[42:43], 31, v13
	v_lshl_add_u64 v[56:57], s[8:9], 0, v[0:1]
	v_lshl_add_u64 v[60:61], v[8:9], 1, v[4:5]
	v_lshl_add_u64 v[62:63], v[2:3], 0, s[0:1]
	v_mov_b32_e32 v65, 0
	v_lshlrev_b32_e32 v0, 1, v44
	s_mov_b32 s51, 2
	v_mov_b32_e32 v31, v30
	v_mov_b32_e32 v32, v30
	v_mov_b32_e32 v33, v30
	v_mov_b32_e32 v26, v30
	v_mov_b32_e32 v27, v30
	v_mov_b32_e32 v28, v30
	v_mov_b32_e32 v29, v30
	v_mov_b32_e32 v22, v30
	v_mov_b32_e32 v23, v30
	v_mov_b32_e32 v24, v30
	v_mov_b32_e32 v25, v30
	v_mov_b32_e32 v18, v30
	v_mov_b32_e32 v19, v30
	v_mov_b32_e32 v20, v30
	v_mov_b32_e32 v21, v30
	v_mov_b32_e32 v14, v30
	v_mov_b32_e32 v15, v30
	v_mov_b32_e32 v16, v30
	v_mov_b32_e32 v17, v30
	v_mov_b32_e32 v10, v30
	v_mov_b32_e32 v11, v30
	v_mov_b32_e32 v12, v30
	v_mov_b32_e32 v13, v30
	v_mov_b32_e32 v6, v30
	v_mov_b32_e32 v7, v30
	v_mov_b32_e32 v8, v30
	v_mov_b32_e32 v9, v30
	v_mov_b32_e32 v2, v30
	v_mov_b32_e32 v3, v30
	v_mov_b32_e32 v4, v30
	v_mov_b32_e32 v5, v30
